# baseline (speedup 1.0000x reference)
.LBB0_818:
	s_waitcnt lgkmcnt(9)
	v_pk_mul_f32 v[196:197], v[16:17], v[130:131]
	v_pk_mul_f32 v[198:199], v[18:19], v[132:133]
	v_pk_fma_f32 v[196:197], v[20:21], v[126:127], v[196:197]
	v_pk_fma_f32 v[198:199], v[22:23], v[128:129], v[198:199]
	v_pk_mul_f32 v[130:131], v[24:25], v[130:131]
	v_pk_add_f32 v[196:197], v[196:197], v[198:199]
	v_pk_fma_f32 v[126:127], v[28:29], v[126:127], v[130:131]
	v_add_f32_e32 v196, v196, v197
	v_pk_mul_f32 v[130:131], v[26:27], v[132:133]
	ds_read_b128 v[166:169], v97 offset:24576
	ds_read_b128 v[170:173], v97 offset:24592
	ds_read_b128 v[150:153], v97 offset:32768
	ds_read_b128 v[134:137], v97 offset:32784
	ds_read_b128 v[158:161], v97 offset:40960
	ds_read_b128 v[146:149], v97 offset:40976
	ds_read_b128 v[162:165], v97 offset:8192
	ds_read_b128 v[154:157], v97 offset:8208
	ds_read_b128 v[138:141], v97
	ds_read_b128 v[142:145], v97 offset:16
	ds_read_b64 v[194:195], v244
	v_add_f32_dpp v196, v196, v196 quad_perm:[1,0,3,2] row_mask:0xf bank_mask:0xf bound_ctrl:1
	v_pk_fma_f32 v[128:129], v[30:31], v[128:129], v[130:131]
	s_nop 0
	v_add_f32_dpp v196, v196, v196 quad_perm:[2,3,0,1] row_mask:0xf bank_mask:0xf bound_ctrl:1
	v_pk_add_f32 v[126:127], v[126:127], v[128:129]
	s_nop 0
	v_add_f32_dpp v196, v196, v196 row_half_mirror row_mask:0xf bank_mask:0xf bound_ctrl:1
	s_waitcnt lgkmcnt(11)
	v_pk_mul_f32 v[128:129], v[118:119], v[196:197] op_sel_hi:[1,0] neg_lo:[0,1] neg_hi:[0,1]
	v_add_f32_e32 v126, v126, v127
	v_pk_fma_f32 v[128:129], v[122:123], v[192:193], v[128:129] op_sel_hi:[1,0,1]
	s_nop 0
	v_pk_fma_f32 v[128:129], v[20:21], v[98:99], v[128:129]
	v_pk_mul_f32 v[20:21], v[120:121], v[196:197] op_sel_hi:[1,0] neg_lo:[0,1] neg_hi:[0,1]
	v_add_f32_dpp v126, v126, v126 quad_perm:[1,0,3,2] row_mask:0xf bank_mask:0xf bound_ctrl:1
	v_pk_fma_f32 v[20:21], v[124:125], v[192:193], v[20:21] op_sel_hi:[1,0,1]
	s_nop 0
	v_pk_fma_f32 v[130:131], v[22:23], v[100:101], v[20:21]
	v_pk_mul_f32 v[20:21], v[102:103], v[196:197] op_sel_hi:[1,0] neg_lo:[0,1] neg_hi:[0,1]
	v_add_f32_dpp v126, v126, v126 quad_perm:[2,3,0,1] row_mask:0xf bank_mask:0xf bound_ctrl:1
	v_pk_fma_f32 v[20:21], v[110:111], v[192:193], v[20:21] op_sel_hi:[1,0,1]
	s_nop 0
	v_pk_fma_f32 v[132:133], v[16:17], v[92:93], v[20:21]
	v_pk_mul_f32 v[16:17], v[104:105], v[196:197] op_sel_hi:[1,0] neg_lo:[0,1] neg_hi:[0,1]
	v_add_f32_dpp v126, v126, v126 row_half_mirror row_mask:0xf bank_mask:0xf bound_ctrl:1
	v_pk_fma_f32 v[16:17], v[112:113], v[192:193], v[16:17] op_sel_hi:[1,0,1]
	s_nop 0
	v_pk_fma_f32 v[196:197], v[18:19], v[94:95], v[16:17]
	v_pk_mul_f32 v[16:17], v[114:115], v[132:133]
	v_pk_mul_f32 v[18:19], v[116:117], v[196:197]
	v_pk_fma_f32 v[16:17], v[106:107], v[128:129], v[16:17]
	v_pk_fma_f32 v[18:19], v[108:109], v[130:131], v[18:19]
	s_nop 0
	v_pk_add_f32 v[16:17], v[16:17], v[18:19]
	v_pk_mul_f32 v[18:19], v[118:119], v[126:127] op_sel_hi:[1,0] neg_lo:[0,1] neg_hi:[0,1]
	s_nop 0
	v_pk_fma_f32 v[18:19], v[122:123], v[192:193], v[18:19] op_sel:[0,1,0]
	s_nop 0
	v_pk_fma_f32 v[28:29], v[28:29], v[98:99], v[18:19]
	v_pk_mul_f32 v[18:19], v[120:121], v[126:127] op_sel_hi:[1,0] neg_lo:[0,1] neg_hi:[0,1]
	s_nop 0
	v_pk_fma_f32 v[18:19], v[124:125], v[192:193], v[18:19] op_sel:[0,1,0]
	s_nop 0
	v_pk_fma_f32 v[30:31], v[30:31], v[100:101], v[18:19]
	v_pk_mul_f32 v[18:19], v[102:103], v[126:127] op_sel_hi:[1,0] neg_lo:[0,1] neg_hi:[0,1]
	s_nop 0
	v_pk_fma_f32 v[18:19], v[110:111], v[192:193], v[18:19] op_sel:[0,1,0]
	s_nop 0
	v_pk_fma_f32 v[24:25], v[24:25], v[92:93], v[18:19]
	v_pk_mul_f32 v[18:19], v[104:105], v[126:127] op_sel_hi:[1,0] neg_lo:[0,1] neg_hi:[0,1]
	s_nop 0
	v_pk_fma_f32 v[18:19], v[112:113], v[192:193], v[18:19] op_sel:[0,1,0]
	s_nop 0
	v_pk_fma_f32 v[26:27], v[26:27], v[94:95], v[18:19]
	v_pk_mul_f32 v[18:19], v[114:115], v[24:25]
	v_pk_mul_f32 v[20:21], v[116:117], v[26:27]
	v_pk_fma_f32 v[18:19], v[106:107], v[28:29], v[18:19]
	v_pk_fma_f32 v[20:21], v[108:109], v[30:31], v[20:21]
	s_nop 0
	v_pk_add_f32 v[18:19], v[18:19], v[20:21]
	s_nop 0
	v_add_f32_e32 v16, v16, v17
	v_add_f32_e32 v17, v18, v19
	s_nop 0
	v_add_f32_dpp v16, v16, v16 quad_perm:[1,0,3,2] row_mask:0xf bank_mask:0xf bound_ctrl:1
	v_add_f32_dpp v17, v17, v17 quad_perm:[1,0,3,2] row_mask:0xf bank_mask:0xf bound_ctrl:1
	s_nop 0
	v_add_f32_dpp v16, v16, v16 quad_perm:[2,3,0,1] row_mask:0xf bank_mask:0xf bound_ctrl:1
	v_add_f32_dpp v17, v17, v17 quad_perm:[2,3,0,1] row_mask:0xf bank_mask:0xf bound_ctrl:1
	s_nop 0
	v_add_f32_dpp v16, v16, v16 row_half_mirror row_mask:0xf bank_mask:0xf bound_ctrl:1
	v_add_f32_dpp v17, v17, v17 row_half_mirror row_mask:0xf bank_mask:0xf bound_ctrl:1
	ds_write_b64 v244, v[16:17] offset:42240
	s_waitcnt lgkmcnt(9)
	v_pk_mul_f32 v[192:193], v[132:133], v[170:171]
	v_pk_mul_f32 v[198:199], v[196:197], v[172:173]
	v_pk_fma_f32 v[192:193], v[128:129], v[166:167], v[192:193]
	v_pk_fma_f32 v[198:199], v[130:131], v[168:169], v[198:199]
	v_pk_mul_f32 v[170:171], v[24:25], v[170:171]
	v_pk_add_f32 v[192:193], v[192:193], v[198:199]
	v_pk_fma_f32 v[166:167], v[28:29], v[166:167], v[170:171]
	v_add_f32_e32 v192, v192, v193
	v_pk_mul_f32 v[170:171], v[26:27], v[172:173]
	ds_read_b128 v[118:121], v97 offset:24832
	ds_read_b128 v[122:125], v97 offset:24848
	ds_read_b128 v[102:105], v97 offset:33024
	ds_read_b128 v[16:19], v97 offset:33040
	ds_read_b128 v[110:113], v97 offset:41216
	ds_read_b128 v[98:101], v97 offset:41232
	ds_read_b128 v[114:117], v97 offset:8448
	ds_read_b128 v[106:109], v97 offset:8464
	ds_read_b128 v[20:23], v97 offset:256
	ds_read_b128 v[92:95], v97 offset:272
	ds_read_b64 v[126:127], v244 offset:256
	v_add_f32_dpp v192, v192, v192 quad_perm:[1,0,3,2] row_mask:0xf bank_mask:0xf bound_ctrl:1
	v_pk_fma_f32 v[168:169], v[30:31], v[168:169], v[170:171]
	s_nop 0
	v_add_f32_dpp v192, v192, v192 quad_perm:[2,3,0,1] row_mask:0xf bank_mask:0xf bound_ctrl:1
	v_pk_add_f32 v[166:167], v[166:167], v[168:169]
	s_nop 0
	v_add_f32_dpp v192, v192, v192 row_half_mirror row_mask:0xf bank_mask:0xf bound_ctrl:1
	s_waitcnt lgkmcnt(11)
	v_pk_mul_f32 v[168:169], v[158:159], v[192:193] op_sel_hi:[1,0] neg_lo:[0,1] neg_hi:[0,1]
	v_add_f32_e32 v166, v166, v167
	v_pk_fma_f32 v[168:169], v[162:163], v[194:195], v[168:169] op_sel_hi:[1,0,1]
	s_nop 0
	v_pk_fma_f32 v[128:129], v[128:129], v[150:151], v[168:169]
	v_pk_mul_f32 v[168:169], v[160:161], v[192:193] op_sel_hi:[1,0] neg_lo:[0,1] neg_hi:[0,1]
	v_add_f32_dpp v166, v166, v166 quad_perm:[1,0,3,2] row_mask:0xf bank_mask:0xf bound_ctrl:1
	v_pk_fma_f32 v[168:169], v[164:165], v[194:195], v[168:169] op_sel_hi:[1,0,1]
	s_nop 0
	v_add_f32_dpp v166, v166, v166 quad_perm:[2,3,0,1] row_mask:0xf bank_mask:0xf bound_ctrl:1
	v_pk_fma_f32 v[130:131], v[130:131], v[152:153], v[168:169]
	v_pk_mul_f32 v[168:169], v[146:147], v[192:193] op_sel_hi:[1,0] neg_lo:[0,1] neg_hi:[0,1]
	v_add_f32_dpp v166, v166, v166 row_half_mirror row_mask:0xf bank_mask:0xf bound_ctrl:1
	v_pk_fma_f32 v[168:169], v[154:155], v[194:195], v[168:169] op_sel_hi:[1,0,1]
	v_pk_mul_f32 v[158:159], v[158:159], v[166:167] op_sel_hi:[1,0] neg_lo:[0,1] neg_hi:[0,1]
	v_pk_fma_f32 v[132:133], v[132:133], v[134:135], v[168:169]
	v_pk_mul_f32 v[168:169], v[148:149], v[192:193] op_sel_hi:[1,0] neg_lo:[0,1] neg_hi:[0,1]
	v_pk_fma_f32 v[158:159], v[162:163], v[194:195], v[158:159] op_sel:[0,1,0]
	v_pk_fma_f32 v[168:169], v[156:157], v[194:195], v[168:169] op_sel_hi:[1,0,1]
	s_nop 0
	v_pk_fma_f32 v[192:193], v[196:197], v[136:137], v[168:169]
	v_pk_fma_f32 v[196:197], v[28:29], v[150:151], v[158:159]
	v_pk_mul_f32 v[28:29], v[160:161], v[166:167] op_sel_hi:[1,0] neg_lo:[0,1] neg_hi:[0,1]
	v_pk_mul_f32 v[168:169], v[142:143], v[132:133]
	v_pk_fma_f32 v[28:29], v[164:165], v[194:195], v[28:29] op_sel:[0,1,0]
	v_pk_mul_f32 v[170:171], v[144:145], v[192:193]
	v_pk_fma_f32 v[198:199], v[30:31], v[152:153], v[28:29]
	v_pk_mul_f32 v[28:29], v[146:147], v[166:167] op_sel_hi:[1,0] neg_lo:[0,1] neg_hi:[0,1]
	v_pk_fma_f32 v[168:169], v[138:139], v[128:129], v[168:169]
	v_pk_fma_f32 v[28:29], v[154:155], v[194:195], v[28:29] op_sel:[0,1,0]
	v_pk_fma_f32 v[170:171], v[140:141], v[130:131], v[170:171]
	v_pk_fma_f32 v[200:201], v[24:25], v[134:135], v[28:29]
	v_pk_mul_f32 v[24:25], v[148:149], v[166:167] op_sel_hi:[1,0] neg_lo:[0,1] neg_hi:[0,1]
	v_pk_add_f32 v[168:169], v[168:169], v[170:171]
	v_pk_fma_f32 v[24:25], v[156:157], v[194:195], v[24:25] op_sel:[0,1,0]
	s_nop 0
	v_pk_fma_f32 v[202:203], v[26:27], v[136:137], v[24:25]
	v_pk_mul_f32 v[24:25], v[142:143], v[200:201]
	v_pk_mul_f32 v[26:27], v[144:145], v[202:203]
	v_pk_fma_f32 v[24:25], v[138:139], v[196:197], v[24:25]
	v_pk_fma_f32 v[26:27], v[140:141], v[198:199], v[26:27]
	s_nop 0
	v_pk_add_f32 v[24:25], v[24:25], v[26:27]
	s_nop 0
	v_add_f32_e32 v25, v24, v25
	v_add_f32_e32 v24, v168, v169
	s_nop 0
	v_add_f32_dpp v25, v25, v25 quad_perm:[1,0,3,2] row_mask:0xf bank_mask:0xf bound_ctrl:1
	v_add_f32_dpp v24, v24, v24 quad_perm:[1,0,3,2] row_mask:0xf bank_mask:0xf bound_ctrl:1
	s_nop 0
	v_add_f32_dpp v25, v25, v25 quad_perm:[2,3,0,1] row_mask:0xf bank_mask:0xf bound_ctrl:1
	v_add_f32_dpp v24, v24, v24 quad_perm:[2,3,0,1] row_mask:0xf bank_mask:0xf bound_ctrl:1
	s_nop 0
	v_add_f32_dpp v25, v25, v25 row_half_mirror row_mask:0xf bank_mask:0xf bound_ctrl:1
	v_add_f32_dpp v24, v24, v24 row_half_mirror row_mask:0xf bank_mask:0xf bound_ctrl:1
	ds_write_b64 v244, v[24:25] offset:42496
	s_waitcnt lgkmcnt(9)
	v_pk_mul_f32 v[168:169], v[132:133], v[122:123]
	v_pk_mul_f32 v[170:171], v[192:193], v[124:125]
	v_pk_fma_f32 v[168:169], v[128:129], v[118:119], v[168:169]
	v_pk_fma_f32 v[170:171], v[130:131], v[120:121], v[170:171]
	v_pk_mul_f32 v[122:123], v[200:201], v[122:123]
	v_pk_add_f32 v[168:169], v[168:169], v[170:171]
	v_pk_fma_f32 v[118:119], v[196:197], v[118:119], v[122:123]
	v_add_f32_e32 v168, v168, v169
	v_pk_mul_f32 v[122:123], v[202:203], v[124:125]
	ds_read_b128 v[158:161], v97 offset:25088
	ds_read_b128 v[162:165], v97 offset:25104
	ds_read_b128 v[28:31], v97 offset:33280
	ds_read_b128 v[24:27], v97 offset:33296
	ds_read_b128 v[150:153], v97 offset:41472
	ds_read_b128 v[142:145], v97 offset:41488
	ds_read_b128 v[154:157], v97 offset:8704
	ds_read_b128 v[146:149], v97 offset:8720
	ds_read_b128 v[134:137], v97 offset:512
	ds_read_b128 v[138:141], v97 offset:528
	ds_read_b64 v[166:167], v244 offset:512
	v_add_f32_dpp v168, v168, v168 quad_perm:[1,0,3,2] row_mask:0xf bank_mask:0xf bound_ctrl:1
	v_pk_fma_f32 v[120:121], v[198:199], v[120:121], v[122:123]
	s_nop 0
	v_add_f32_dpp v168, v168, v168 quad_perm:[2,3,0,1] row_mask:0xf bank_mask:0xf bound_ctrl:1
	v_pk_add_f32 v[118:119], v[118:119], v[120:121]
	s_nop 0
	v_add_f32_dpp v194, v168, v168 row_half_mirror row_mask:0xf bank_mask:0xf bound_ctrl:1
	v_add_f32_e32 v118, v118, v119
	s_waitcnt lgkmcnt(11)
	v_pk_mul_f32 v[120:121], v[110:111], v[194:195] op_sel_hi:[1,0] neg_lo:[0,1] neg_hi:[0,1]
	v_add_f32_dpp v118, v118, v118 quad_perm:[1,0,3,2] row_mask:0xf bank_mask:0xf bound_ctrl:1
	v_pk_fma_f32 v[120:121], v[114:115], v[126:127], v[120:121] op_sel_hi:[1,0,1]
	v_add_f32_dpp v118, v118, v118 quad_perm:[2,3,0,1] row_mask:0xf bank_mask:0xf bound_ctrl:1
	v_pk_fma_f32 v[168:169], v[128:129], v[102:103], v[120:121]
	v_pk_mul_f32 v[120:121], v[112:113], v[194:195] op_sel_hi:[1,0] neg_lo:[0,1] neg_hi:[0,1]
	v_add_f32_dpp v118, v118, v118 row_half_mirror row_mask:0xf bank_mask:0xf bound_ctrl:1
	v_pk_fma_f32 v[120:121], v[116:117], v[126:127], v[120:121] op_sel_hi:[1,0,1]
	v_pk_mul_f32 v[110:111], v[110:111], v[118:119] op_sel_hi:[1,0] neg_lo:[0,1] neg_hi:[0,1]
	v_pk_fma_f32 v[170:171], v[130:131], v[104:105], v[120:121]
	v_pk_mul_f32 v[120:121], v[98:99], v[194:195] op_sel_hi:[1,0] neg_lo:[0,1] neg_hi:[0,1]
	v_pk_mul_f32 v[98:99], v[98:99], v[118:119] op_sel_hi:[1,0] neg_lo:[0,1] neg_hi:[0,1]
	v_pk_fma_f32 v[120:121], v[106:107], v[126:127], v[120:121] op_sel_hi:[1,0,1]
	v_pk_fma_f32 v[98:99], v[106:107], v[126:127], v[98:99] op_sel:[0,1,0]
	v_pk_fma_f32 v[172:173], v[132:133], v[16:17], v[120:121]
	v_pk_mul_f32 v[120:121], v[100:101], v[194:195] op_sel_hi:[1,0] neg_lo:[0,1] neg_hi:[0,1]
	v_pk_fma_f32 v[110:111], v[114:115], v[126:127], v[110:111] op_sel:[0,1,0]
	v_pk_fma_f32 v[200:201], v[200:201], v[16:17], v[98:99]
	v_pk_mul_f32 v[16:17], v[100:101], v[118:119] op_sel_hi:[1,0] neg_lo:[0,1] neg_hi:[0,1]
	v_pk_fma_f32 v[120:121], v[108:109], v[126:127], v[120:121] op_sel_hi:[1,0,1]
	v_pk_fma_f32 v[196:197], v[196:197], v[102:103], v[110:111]
	v_pk_mul_f32 v[102:103], v[112:113], v[118:119] op_sel_hi:[1,0] neg_lo:[0,1] neg_hi:[0,1]
	v_pk_fma_f32 v[16:17], v[108:109], v[126:127], v[16:17] op_sel:[0,1,0]
	v_pk_fma_f32 v[194:195], v[192:193], v[18:19], v[120:121]
	v_pk_fma_f32 v[102:103], v[116:117], v[126:127], v[102:103] op_sel:[0,1,0]
	v_pk_fma_f32 v[202:203], v[202:203], v[18:19], v[16:17]
	v_pk_mul_f32 v[120:121], v[92:93], v[172:173]
	v_pk_mul_f32 v[122:123], v[94:95], v[194:195]
	v_pk_fma_f32 v[198:199], v[198:199], v[104:105], v[102:103]
	v_pk_mul_f32 v[16:17], v[92:93], v[200:201]
	v_pk_mul_f32 v[18:19], v[94:95], v[202:203]
	v_pk_fma_f32 v[120:121], v[20:21], v[168:169], v[120:121]
	v_pk_fma_f32 v[122:123], v[22:23], v[170:171], v[122:123]
	v_pk_fma_f32 v[16:17], v[20:21], v[196:197], v[16:17]
	v_pk_fma_f32 v[18:19], v[22:23], v[198:199], v[18:19]
	v_pk_add_f32 v[120:121], v[120:121], v[122:123]
	v_pk_add_f32 v[16:17], v[16:17], v[18:19]
	s_nop 0
	v_add_f32_e32 v17, v16, v17
	v_add_f32_e32 v16, v120, v121
	s_nop 0
	v_add_f32_dpp v17, v17, v17 quad_perm:[1,0,3,2] row_mask:0xf bank_mask:0xf bound_ctrl:1
	v_add_f32_dpp v16, v16, v16 quad_perm:[1,0,3,2] row_mask:0xf bank_mask:0xf bound_ctrl:1
	s_nop 0
	v_add_f32_dpp v17, v17, v17 quad_perm:[2,3,0,1] row_mask:0xf bank_mask:0xf bound_ctrl:1
	v_add_f32_dpp v16, v16, v16 quad_perm:[2,3,0,1] row_mask:0xf bank_mask:0xf bound_ctrl:1
	s_nop 0
	v_add_f32_dpp v17, v17, v17 row_half_mirror row_mask:0xf bank_mask:0xf bound_ctrl:1
	v_add_f32_dpp v16, v16, v16 row_half_mirror row_mask:0xf bank_mask:0xf bound_ctrl:1
	ds_write_b64 v244, v[16:17] offset:42752
	s_and_b32 s0, s6, 0x700
	v_or_b32_e32 v16, s0, v174
	v_lshlrev_b32_e32 v16, 2, v16
	ds_read_b128 v[126:129], v16 offset:24576
	ds_read_b128 v[130:133], v16 offset:24592
	ds_read_b128 v[98:101], v16 offset:32768
	ds_read_b128 v[92:95], v16 offset:32784
	ds_read_b128 v[118:121], v16 offset:40960
	ds_read_b128 v[102:105], v16 offset:40976
	ds_read_b128 v[122:125], v16 offset:8192
	ds_read_b128 v[110:113], v16 offset:8208
	ds_read_b128 v[106:109], v16
	ds_read_b128 v[114:117], v16 offset:16
	v_lshl_add_u32 v16, s0, 2, v236
	ds_read_b64 v[192:193], v16 offset:16384
	s_waitcnt lgkmcnt(14)
	v_pk_mul_f32 v[16:17], v[172:173], v[162:163]
	v_pk_mul_f32 v[18:19], v[194:195], v[164:165]
	v_pk_fma_f32 v[16:17], v[168:169], v[158:159], v[16:17]
	v_pk_fma_f32 v[18:19], v[170:171], v[160:161], v[18:19]
	v_pk_mul_f32 v[20:21], v[202:203], v[164:165]
	v_pk_add_f32 v[16:17], v[16:17], v[18:19]
	v_pk_fma_f32 v[20:21], v[198:199], v[160:161], v[20:21]
	v_add_f32_e32 v16, v16, v17
	s_nop 1
	v_add_f32_dpp v16, v16, v16 quad_perm:[1,0,3,2] row_mask:0xf bank_mask:0xf bound_ctrl:1
	s_nop 1
	v_add_f32_dpp v16, v16, v16 quad_perm:[2,3,0,1] row_mask:0xf bank_mask:0xf bound_ctrl:1
	s_nop 1
	v_add_f32_dpp v18, v16, v16 row_half_mirror row_mask:0xf bank_mask:0xf bound_ctrl:1
	v_pk_mul_f32 v[16:17], v[200:201], v[162:163]
	s_nop 0
	v_pk_fma_f32 v[16:17], v[196:197], v[158:159], v[16:17]
	s_nop 0
	v_pk_add_f32 v[16:17], v[16:17], v[20:21]
	s_nop 0
	v_add_f32_e32 v16, v16, v17
	s_nop 1
	v_add_f32_dpp v16, v16, v16 quad_perm:[1,0,3,2] row_mask:0xf bank_mask:0xf bound_ctrl:1
	s_nop 1
	v_add_f32_dpp v16, v16, v16 quad_perm:[2,3,0,1] row_mask:0xf bank_mask:0xf bound_ctrl:1
	s_nop 1
	v_add_f32_dpp v158, v16, v16 row_half_mirror row_mask:0xf bank_mask:0xf bound_ctrl:1
	v_pk_mul_f32 v[16:17], v[150:151], v[18:19] op_sel_hi:[1,0] neg_lo:[0,1] neg_hi:[0,1]
	v_pk_mul_f32 v[150:151], v[150:151], v[158:159] op_sel_hi:[1,0] neg_lo:[0,1] neg_hi:[0,1]
	s_waitcnt lgkmcnt(11)
	v_pk_fma_f32 v[16:17], v[154:155], v[166:167], v[16:17] op_sel_hi:[1,0,1]
	v_pk_fma_f32 v[150:151], v[154:155], v[166:167], v[150:151] op_sel:[0,1,0]
	v_pk_fma_f32 v[20:21], v[168:169], v[28:29], v[16:17]
	v_pk_mul_f32 v[16:17], v[152:153], v[18:19] op_sel_hi:[1,0] neg_lo:[0,1] neg_hi:[0,1]
	v_pk_fma_f32 v[28:29], v[196:197], v[28:29], v[150:151]
	v_pk_fma_f32 v[16:17], v[156:157], v[166:167], v[16:17] op_sel_hi:[1,0,1]
	v_pk_mul_f32 v[150:151], v[152:153], v[158:159] op_sel_hi:[1,0] neg_lo:[0,1] neg_hi:[0,1]
	v_pk_fma_f32 v[22:23], v[170:171], v[30:31], v[16:17]
	v_pk_mul_f32 v[16:17], v[142:143], v[18:19] op_sel_hi:[1,0] neg_lo:[0,1] neg_hi:[0,1]
	v_pk_mul_f32 v[142:143], v[142:143], v[158:159] op_sel_hi:[1,0] neg_lo:[0,1] neg_hi:[0,1]
	v_pk_fma_f32 v[16:17], v[146:147], v[166:167], v[16:17] op_sel_hi:[1,0,1]
	v_pk_fma_f32 v[142:143], v[146:147], v[166:167], v[142:143] op_sel:[0,1,0]
	v_pk_fma_f32 v[16:17], v[172:173], v[24:25], v[16:17]
	v_pk_mul_f32 v[18:19], v[144:145], v[18:19] op_sel_hi:[1,0] neg_lo:[0,1] neg_hi:[0,1]
	v_pk_fma_f32 v[24:25], v[200:201], v[24:25], v[142:143]
	v_pk_mul_f32 v[142:143], v[144:145], v[158:159] op_sel_hi:[1,0] neg_lo:[0,1] neg_hi:[0,1]
	v_pk_fma_f32 v[18:19], v[148:149], v[166:167], v[18:19] op_sel_hi:[1,0,1]
	v_pk_fma_f32 v[142:143], v[148:149], v[166:167], v[142:143] op_sel:[0,1,0]
	v_pk_fma_f32 v[18:19], v[194:195], v[26:27], v[18:19]
	v_pk_mul_f32 v[160:161], v[138:139], v[16:17]
	v_pk_fma_f32 v[150:151], v[156:157], v[166:167], v[150:151] op_sel:[0,1,0]
	v_pk_fma_f32 v[26:27], v[202:203], v[26:27], v[142:143]
	v_pk_mul_f32 v[138:139], v[138:139], v[24:25]
	v_pk_fma_f32 v[160:161], v[134:135], v[20:21], v[160:161]
	v_pk_mul_f32 v[162:163], v[140:141], v[18:19]
	v_pk_fma_f32 v[30:31], v[198:199], v[30:31], v[150:151]
	v_pk_fma_f32 v[134:135], v[134:135], v[28:29], v[138:139]
	v_pk_mul_f32 v[138:139], v[140:141], v[26:27]
	v_pk_fma_f32 v[162:163], v[136:137], v[22:23], v[162:163]
	v_pk_fma_f32 v[136:137], v[136:137], v[30:31], v[138:139]
	v_pk_add_f32 v[160:161], v[160:161], v[162:163]
	v_pk_add_f32 v[134:135], v[134:135], v[136:137]
	s_nop 0
	v_add_f32_e32 v135, v134, v135
	v_add_f32_e32 v134, v160, v161
	s_nop 0
	v_add_f32_dpp v135, v135, v135 quad_perm:[1,0,3,2] row_mask:0xf bank_mask:0xf bound_ctrl:1
	v_add_f32_dpp v134, v134, v134 quad_perm:[1,0,3,2] row_mask:0xf bank_mask:0xf bound_ctrl:1
	s_nop 0
	v_add_f32_dpp v135, v135, v135 quad_perm:[2,3,0,1] row_mask:0xf bank_mask:0xf bound_ctrl:1
	v_add_f32_dpp v134, v134, v134 quad_perm:[2,3,0,1] row_mask:0xf bank_mask:0xf bound_ctrl:1
	s_nop 0
	v_add_f32_dpp v135, v135, v135 row_half_mirror row_mask:0xf bank_mask:0xf bound_ctrl:1
	v_add_f32_dpp v134, v134, v134 row_half_mirror row_mask:0xf bank_mask:0xf bound_ctrl:1
	ds_write_b64 v244, v[134:135] offset:43008
	s_branch .LBB0_817
